# workgroup index re-derived from physical XCC id + arrival rank so XCD-local sync holds under any dispatch order (fallback only when XCCs are unevenly populated)
# baseline (speedup 1.0000x reference)
_Z8yoco_fwd6Params:
	s_load_dwordx16 s[76:91], s[0:1], 0x80
	s_load_dword s33, s[0:1], 0xc8
	s_load_dwordx2 s[72:73], s[0:1], 0xc0
	s_add_u32 s20, s0, 0xc0
	v_and_b32_e32 v218, 0x3ff, v0
	s_addc_u32 s21, s1, 0
	v_cmp_gt_u32_e32 vcc, 2, v218
	s_and_saveexec_b64 s[4:5], vcc
	v_lshl_add_u32 v1, v218, 2, 0
	v_add_u32_e32 v1, 0x20000, v1
	v_mov_b32_e32 v2, 0
	ds_write_b32 v1, v2
	s_or_b64 exec, exec, s[4:5]
	s_load_dwordx16 s[4:19], s[0:1], 0x0
	s_waitcnt lgkmcnt(0)
	s_barrier
	s_add_u32 s38, s90, 0x280000
	v_writelane_b32 v253, s4, 0
	s_addc_u32 s39, s91, 0
	v_cmp_eq_u32_e64 s[64:65], 0, v218
	v_writelane_b32 v253, s5, 1
	v_writelane_b32 v253, s6, 2
	v_writelane_b32 v253, s7, 3
	v_writelane_b32 v253, s8, 4
	v_writelane_b32 v253, s9, 5
	v_writelane_b32 v253, s10, 6
	v_writelane_b32 v253, s11, 7
	v_writelane_b32 v253, s12, 8
	v_writelane_b32 v253, s13, 9
	v_writelane_b32 v253, s14, 10
	v_writelane_b32 v253, s15, 11
	v_writelane_b32 v253, s16, 12
	v_writelane_b32 v253, s17, 13
	v_writelane_b32 v253, s18, 14
	v_writelane_b32 v253, s19, 15
	s_load_dwordx16 s[4:19], s[0:1], 0x40
	s_getreg_b32 s0, hwreg(HW_REG_XCC_ID, 0, 4)
	s_and_b32 s3, s0, 15
	s_mov_b32 s1, 0
	s_waitcnt lgkmcnt(0)
	v_writelane_b32 v253, s4, 16
	s_nop 1
	v_writelane_b32 v253, s5, 17
	v_writelane_b32 v253, s6, 18
	v_writelane_b32 v253, s7, 19
	v_writelane_b32 v253, s8, 20
	v_writelane_b32 v253, s9, 21
	v_writelane_b32 v253, s10, 22
	v_writelane_b32 v253, s11, 23
	v_writelane_b32 v253, s12, 24
	v_writelane_b32 v253, s13, 25
	v_writelane_b32 v253, s14, 26
	v_writelane_b32 v253, s15, 27
	v_writelane_b32 v253, s16, 28
	v_writelane_b32 v253, s17, 29
	v_writelane_b32 v253, s18, 30
	v_writelane_b32 v253, s19, 31
	s_and_saveexec_b64 s[22:23], s[64:65]
	s_cbranch_execz .LBB0_5
	s_mov_b64 s[24:25], exec
	v_mbcnt_lo_u32_b32 v1, s24, 0
	v_mbcnt_hi_u32_b32 v1, s25, v1
	v_cmp_eq_u32_e32 vcc, 0, v1
	s_and_b64 s[26:27], exec, vcc
	s_mov_b64 exec, s[26:27]
	s_cbranch_execz .LBB0_5
	s_lshl_b32 s0, s3, 8
	s_bcnt1_i32_b64 s24, s[24:25]
	v_mov_b32_e32 v1, s0
	v_mov_b32_e32 v2, s24
	global_atomic_add v2, v1, v2, s[38:39] offset:1024 sc0
	v_mov_b32_e32 v1, 0x20008
	s_waitcnt vmcnt(0)
	ds_write_b32 v1, v2

.Lcen_done:
	s_lshl_b32 s98, s3, 8
	s_add_i32 s98, s98, 0x400
	v_mov_b32_e32 v2, s98
	global_load_dword v2, v2, s[38:39] sc1
	v_mov_b32_e32 v1, 0x20008
	ds_read_b32 v1, v1
	s_lshr_b32 s99, s72, 3
	s_waitcnt vmcnt(0) lgkmcnt(0)
	v_cmp_ne_u32_e32 vcc, s99, v2
	v_cmp_le_u32_e64 s[100:101], s99, v1
	s_nop 3
	s_or_b64 vcc, vcc, s[100:101]
	s_cmp_gt_u32 s3, 7
	s_cselect_b64 s[100:101], -1, 0
	s_or_b64 vcc, vcc, s[100:101]
	s_and_b64 vcc, vcc, exec
	s_cbranch_vccz .Lcensus_ok
	v_mov_b32_e32 v1, 0x3780
	v_mov_b32_e32 v2, 1
	global_atomic_or v1, v2, s[38:39]

.LBB0_138:
	s_or_b64 exec, exec, s[0:1]
	v_mov_b32_e32 v1, 0x3780
	global_load_dword v1, v1, s[38:39] sc1
	s_waitcnt vmcnt(0)
	v_readfirstlane_b32 s98, v1
	s_nop 3
	s_cmp_eq_u32 s98, 0
	s_cselect_b32 s101, 1, 0
	v_mov_b32_e32 v1, 0x20008
	ds_read_b32 v1, v1
	s_waitcnt lgkmcnt(0)
	v_readfirstlane_b32 s98, v1
	s_nop 3
	s_lshl_b32 s98, s98, 3
	s_add_i32 s98, s98, s3
	s_cmp_lg_u32 s101, 0
	s_cselect_b32 s2, s98, s2
	s_cmpk_lt_i32 s2, 0x200
	s_cselect_b64 s[4:5], -1, 0
	v_writelane_b32 v253, s4, 50
	s_lshl_b32 s1, s2, 6
	s_and_b32 s1, s1, 0x1c0
	v_writelane_b32 v253, s5, 51
	s_ashr_i32 s4, s2, 3
	s_add_i32 s1, s1, s4
	s_ashr_i32 s5, s1, 2
	s_lshl_b32 s1, s4, 1
	s_and_b32 s1, s1, 6
	v_writelane_b32 v253, s1, 52
	s_ashr_i32 s1, s5, 31
	s_add_u32 s68, s26, 0x280200
	s_addc_u32 s69, s27, 0
	s_add_u32 s70, s26, 0x280400
	s_addc_u32 s71, s27, 0
	s_add_u32 s66, s26, 0x280500
	s_addc_u32 s67, s27, 0
	s_add_u32 s34, s26, 0x280600
	s_addc_u32 s35, s27, 0
	s_add_u32 s36, s26, 0x280700
	s_addc_u32 s37, s27, 0
	s_add_u32 s56, s26, 0x280800
	s_addc_u32 s57, s27, 0
	s_add_u32 s58, s26, 0x280900
	s_addc_u32 s59, s27, 0
	s_add_u32 s60, s26, 0x280a00
	s_addc_u32 s61, s27, 0
	s_add_u32 s76, s26, 0x280b00
	s_addc_u32 s77, s27, 0
	s_add_u32 s78, s26, 0x280c00
	s_addc_u32 s79, s27, 0
	s_add_u32 s80, s26, 0x280d00
	s_addc_u32 s81, s27, 0
	s_add_u32 s82, s26, 0x280e00
	s_addc_u32 s83, s27, 0
	s_add_u32 s84, s26, 0x280f00
	s_addc_u32 s85, s27, 0
	s_add_u32 s86, s26, 0x281000
	s_addc_u32 s87, s27, 0
	s_add_u32 s88, s26, 0x281100
	s_addc_u32 s89, s27, 0
	s_add_u32 s90, s26, 0x281200
	s_addc_u32 s91, s27, 0
	s_add_u32 s92, s26, 0x281300
	s_addc_u32 s93, s27, 0
	s_mul_i32 s0, s73, s72
	v_writelane_b32 v253, s5, 54
	s_cmp_eq_u32 s3, 15
	v_writelane_b32 v253, s1, 56
	s_mul_i32 s94, s0, s33
	s_cselect_b64 s[0:1], -1, 0
	v_writelane_b32 v253, s0, 58
	s_cmp_eq_u32 s3, 14
	s_movk_i32 s53, 0x161
	v_writelane_b32 v253, s1, 59
	s_cselect_b64 s[0:1], -1, 0
	v_writelane_b32 v253, s0, 60
	s_cmp_eq_u32 s3, 13
	v_mov_b32_e32 v177, 0
	v_writelane_b32 v253, s1, 61
	s_cselect_b64 s[0:1], -1, 0
	v_writelane_b32 v253, s0, 62
	s_cmp_eq_u32 s3, 12
	v_mov_b32_e32 v220, 0x358637bd
	v_writelane_b32 v253, s1, 63
	s_cselect_b64 s[0:1], -1, 0
	v_writelane_b32 v254, s0, 0
	s_cmp_eq_u32 s3, 11
	v_writelane_b32 v253, s60, 16
	v_writelane_b32 v254, s1, 1
	s_cselect_b64 s[0:1], -1, 0
	v_writelane_b32 v254, s0, 2
	s_cmp_eq_u32 s3, 10
	v_mov_b32_e32 v221, 1
	v_writelane_b32 v254, s1, 3
	s_cselect_b64 s[0:1], -1, 0
	v_writelane_b32 v254, s0, 4
	s_cmp_eq_u32 s3, 9
	v_mbcnt_hi_u32_b32 v219, -1, v51
	v_writelane_b32 v254, s1, 5
	s_cselect_b64 s[0:1], -1, 0
	v_writelane_b32 v254, s0, 6
	s_cmp_eq_u32 s3, 8
	v_mov_b64_e32 v[178:179], 0x1ff
	v_writelane_b32 v254, s1, 7
	s_cselect_b64 s[0:1], -1, 0
	v_writelane_b32 v254, s0, 8
	s_cmp_eq_u32 s3, 7
	v_mov_b64_e32 v[180:181], 0x200
	v_writelane_b32 v254, s1, 9
	s_cselect_b64 s[0:1], -1, 0
	v_writelane_b32 v254, s0, 10
	s_cmp_eq_u32 s3, 6
	v_mov_b64_e32 v[182:183], 0xb00
	v_writelane_b32 v254, s1, 11
	s_cselect_b64 s[0:1], -1, 0
	v_writelane_b32 v254, s0, 12
	s_cmp_eq_u32 s3, 5
	v_mov_b64_e32 v[184:185], 0xaff
	v_writelane_b32 v254, s1, 13
	s_cselect_b64 s[0:1], -1, 0
	v_writelane_b32 v254, s0, 14
	s_cmp_eq_u32 s3, 4
	s_mov_b32 s17, 0
	v_writelane_b32 v254, s1, 15
	s_cselect_b64 s[0:1], -1, 0
	v_writelane_b32 v254, s0, 16
	s_cmp_eq_u32 s3, 3
	s_mov_b64 s[14:15], 0x80
	v_writelane_b32 v254, s1, 17
	s_cselect_b64 s[0:1], -1, 0
	v_writelane_b32 v254, s0, 18
	s_cmp_eq_u32 s3, 2
	v_writelane_b32 v253, s61, 17
	v_writelane_b32 v254, s1, 19
	s_cselect_b64 s[0:1], -1, 0
	v_writelane_b32 v254, s0, 20
	s_cmp_eq_u32 s3, 1
	s_barrier
	v_writelane_b32 v254, s1, 21
	s_cselect_b64 s[0:1], -1, 0
	v_writelane_b32 v254, s0, 22
	s_cmp_eq_u32 s3, 0
	s_nop 0
	v_writelane_b32 v254, s1, 23
	s_cselect_b64 s[0:1], -1, 0
	v_writelane_b32 v254, s0, 24
	s_nop 1
	v_writelane_b32 v254, s1, 25
	s_lshl_b32 s0, s3, 8
	s_add_u32 s0, s38, s0
	s_addc_u32 s1, s39, 0
	s_add_u32 s4, s0, 0x1400
	s_addc_u32 s5, s1, 0
	v_writelane_b32 v254, s4, 26
	s_add_u32 s0, s0, 0x2400
	s_addc_u32 s1, s1, 0
	v_writelane_b32 v254, s5, 27
	v_writelane_b32 v254, s0, 28
	s_nop 1
	v_writelane_b32 v254, s1, 29
	s_add_u32 s0, s26, 0x283400
	s_addc_u32 s1, s27, 0
	v_writelane_b32 v254, s0, 30
	s_nop 1
	v_writelane_b32 v254, s1, 31
	s_add_u32 s0, s26, 0x283500
	s_addc_u32 s1, s27, 0
	v_writelane_b32 v254, s0, 32
	s_ashr_i32 s3, s2, 31
	s_ashr_i32 s73, s72, 31
	v_writelane_b32 v254, s1, 33
	s_lshr_b32 s0, s3, 29
	s_add_i32 s0, s2, s0
	s_ashr_i32 s7, s0, 3
	s_and_b32 s0, s0, -8
	s_sub_i32 s8, s2, s0
	s_cmp_gt_i32 s8, -1
	s_cselect_b64 s[0:1], -1, 0
	s_lshl_b32 s4, s8, 6
	v_writelane_b32 v254, s0, 34
	s_cmpk_lt_i32 s2, 0xb00
	s_nop 0
	v_writelane_b32 v254, s1, 35
	s_cselect_b64 s[0:1], -1, 0
	v_writelane_b32 v254, s0, 36
	s_cmp_lt_i32 s8, 0
	s_nop 0
	v_writelane_b32 v254, s1, 37
	s_cselect_b64 s[0:1], -1, 0
	v_writelane_b32 v254, s0, 38
	s_nop 1
	v_writelane_b32 v254, s1, 39
	s_and_b64 s[0:1], s[0:1], exec
	s_mul_i32 s0, s8, 0x41
	s_cselect_b32 s0, s0, s4
	s_cselect_b32 s1, s53, 0x160
	s_add_i32 s5, s0, s7
	s_ashr_i32 s0, s5, 31
	v_writelane_b32 v254, s0, 40
	s_lshr_b32 s0, s0, 27
	s_add_i32 s0, s5, s0
	s_and_b32 s4, s0, 0xffe0
	s_sub_i32 s4, s5, s4
	v_writelane_b32 v254, s5, 42
	s_bfe_i32 s5, s4, 0x80000
	s_bfe_u32 s5, s5, 0x3000c
	s_add_i32 s5, s4, s5
	s_and_b32 s6, s5, 0xf8
	s_sub_i32 s4, s4, s6
	s_ashr_i32 s0, s0, 5
	s_lshl_b32 s0, s0, 3
	s_sext_i32_i8 s4, s4
	s_add_i32 s95, s0, s4
	s_mul_i32 s0, s8, s1
	s_add_i32 s0, s0, s7
	s_mul_hi_i32 s1, s0, 0x2e8ba2e9
	s_lshr_b32 s4, s1, 31
	s_ashr_i32 s1, s1, 5
	s_add_i32 s1, s1, s4
	s_mul_i32 s4, s1, 0xb0
	s_sub_i32 s0, s0, s4
	s_bfe_u32 s4, s0, 0x3001c
	s_add_i32 s4, s0, s4
	s_and_b32 s6, s4, 0xfff8
	s_sub_i32 s0, s0, s6
	s_lshl_b32 s1, s1, 3
	s_sext_i32_i16 s0, s0
	v_writelane_b32 v254, s8, 44
	s_add_i32 s8, s1, s0
	s_bfe_i32 s0, s5, 0x80000
	s_sext_i32_i16 s1, s0
	s_sext_i32_i16 s0, s4
	v_writelane_b32 v254, s7, 45
	s_ashr_i32 s4, s0, 3
	s_lshr_b32 s0, s0, 3
	v_writelane_b32 v254, s4, 46
	s_bfe_i64 s[4:5], s[0:1], 0x100000
	v_writelane_b32 v254, s4, 47
	s_ashr_i32 s0, s1, 3
	s_mov_b64 s[6:7], -1
	v_writelane_b32 v254, s5, 48
	v_writelane_b32 v254, s0, 49
	s_lshr_b32 s0, s1, 3
	s_bfe_i64 s[0:1], s[0:1], 0x100000
	v_writelane_b32 v254, s0, 50
	s_nop 1
	v_writelane_b32 v254, s1, 51
	s_ashr_i32 s0, s8, 31
	v_writelane_b32 v254, s0, 52
	s_ashr_i32 s0, s95, 31
	v_writelane_b32 v254, s0, 53
	s_add_i32 s0, 0, 0x20000
	v_writelane_b32 v254, s0, 54
	s_add_i32 s0, 0, 0x20004
	v_writelane_b32 v254, s0, 55
	v_writelane_b32 v254, s94, 56
	v_writelane_b32 v254, s68, 57
	s_mov_b32 s0, 0
	s_nop 0
	v_writelane_b32 v254, s69, 58
	v_writelane_b32 v254, s70, 59
	s_nop 1
	v_writelane_b32 v254, s71, 60
	v_writelane_b32 v254, s66, 61
	s_nop 1
	v_writelane_b32 v254, s67, 62
	v_writelane_b32 v254, s34, 63
	s_nop 1
	v_writelane_b32 v255, s35, 0
	v_writelane_b32 v255, s56, 1
	s_nop 1
	v_writelane_b32 v255, s57, 2
	v_writelane_b32 v255, s58, 3
	s_nop 1
	v_writelane_b32 v255, s59, 4
	v_writelane_b32 v255, s95, 5
	v_writelane_b32 v255, s8, 6
	v_writelane_b32 v255, s36, 7
	s_nop 1
	v_writelane_b32 v255, s37, 8
	s_branch .LBB0_141
